# mixer first-grab stagger 6.8us (2 x s_sleep 127) for workgroups 256..511 (was 10us)
# speedup vs baseline: 1.0066x; 1.0001x over previous
.LBB0_299:
	s_or_b64 exec, exec, s[4:5]
	v_readlane_b32 s4, v254, 57
	v_readlane_b32 s5, v254, 58
	s_lshl_b32 s90, s4, 4
	s_lshl_b64 s[4:5], s[90:91], 2
	s_add_u32 s4, s42, s4
	s_addc_u32 s5, s43, s5
	v_readlane_b32 s6, v254, 29
	s_add_u32 s6, s4, s6
	s_addc_u32 s7, s5, 0
	v_writelane_b32 v254, s6, 61
	s_barrier
	s_nop 0
	v_writelane_b32 v254, s7, 62
	s_nop 0
	v_readlane_b32 s6, v254, 31
	s_add_u32 s6, s4, s6
	s_addc_u32 s7, s5, 0
	v_writelane_b32 v254, s6, 63
	s_nop 1
	v_writelane_b32 v255, s7, 0
	v_readlane_b32 s6, v254, 33
	s_add_u32 s6, s4, s6
	s_addc_u32 s7, s5, 0
	v_writelane_b32 v255, s6, 1
	s_nop 1
	v_writelane_b32 v255, s7, 2
	v_readlane_b32 s6, v254, 35
	s_add_u32 s6, s4, s6
	s_addc_u32 s7, s5, 0
	v_writelane_b32 v255, s6, 3
	s_nop 1
	v_writelane_b32 v255, s7, 4
	v_readlane_b32 s6, v254, 37
	s_add_u32 s6, s4, s6
	s_addc_u32 s7, s5, 0
	v_writelane_b32 v255, s6, 5
	s_nop 1
	v_writelane_b32 v255, s7, 6
	v_readlane_b32 s6, v254, 39
	s_add_u32 s6, s4, s6
	s_addc_u32 s7, s5, 0
	v_writelane_b32 v255, s6, 7
	s_nop 1
	v_writelane_b32 v255, s7, 8
	v_readlane_b32 s6, v254, 41
	s_add_u32 s6, s4, s6
	s_addc_u32 s7, s5, 0
	v_writelane_b32 v255, s6, 9
	s_nop 1
	v_writelane_b32 v255, s7, 10
	v_readlane_b32 s6, v254, 43
	s_add_u32 s4, s4, s6
	s_addc_u32 s5, s5, 0
	v_writelane_b32 v255, s4, 11
	s_nop 1
	v_writelane_b32 v255, s5, 12
	v_readlane_b32 s6, v254, 13
	s_cmpk_lt_u32 s6, 0x100
	s_cbranch_scc1 .Lmx_nodelay
	s_sleep 127
	s_sleep 127
.Lmx_nodelay:
	s_branch .LBB0_302
